# attention staging: the lane^1 exchange of the K row sum of squares is a DPP quad_perm add instead of ds_bpermute + LDS wait
# speedup vs baseline: 1.0032x; 1.0032x over previous
.LBB0_348:
	ds_read_b128 v[24:27], v242 offset:16
	ds_read_b128 v[28:31], v242 offset:144
	s_bfe_u32 s88, s33, 0x40002
	s_lshl_b32 s68, s88, 7
	v_add_u32_e32 v0, s68, v186
	v_max_i32_e32 v0, 0, v0
	v_lshlrev_b32_e32 v96, 7, v0
	v_lshl_add_u64 v[48:49], v[142:143], 0, v[96:97]
	v_lshl_add_u64 v[98:99], v[144:145], 0, v[96:97]
	s_add_i32 s58, s68, 0xffffff80
	v_add_u32_e32 v230, s58, v250
	v_lshl_add_u32 v230, v230, 7, v248
	v_max_i32_e32 v231, v248, v230
	global_load_dwordx4 v[116:119], v231, s[82:83]
	global_load_dwordx4 v[154:157], v231, s[92:93]
	v_add_u32_e32 v230, 0x400, v230
	v_max_i32_e32 v231, v248, v230
	global_load_dwordx4 v[44:47], v231, s[82:83]
	global_load_dwordx4 v[68:71], v231, s[92:93]
	v_add_u32_e32 v230, 0x400, v230
	v_max_i32_e32 v231, v248, v230
	global_load_dwordx4 v[158:161], v231, s[82:83]
	global_load_dwordx4 v[162:165], v231, s[92:93]
	v_add_u32_e32 v230, 0x400, v230
	v_max_i32_e32 v231, v248, v230
	global_load_dwordx4 v[40:43], v231, s[82:83]
	global_load_dwordx4 v[48:51], v231, s[92:93]
	ds_read_b128 v[72:75], v242
	ds_read_b128 v[16:19], v242 offset:48
	ds_read_b128 v[32:35], v242 offset:32
	ds_read_b128 v[20:23], v242 offset:176
	ds_read_b128 v[36:39], v242 offset:160
	ds_read_b128 v[76:79], v242 offset:128
	s_mov_b32 s0, s97
	s_and_b32 s97, s90, 12
	s_and_b32 s89, s96, 0xfffff800
	v_readlane_b32 s55, v255, 14
	s_waitcnt vmcnt(12)
	v_and_b32_e32 v224, 63, v251
	v_lshrrev_b32_e32 v225, 3, v224
	s_movk_i32 s58, 0x90
	v_mul_u32_u24_e32 v226, 0x1200, v254
	v_add_u32_e32 v226, 0x12000, v226
	v_and_b32_e32 v227, 7, v224
	v_lshlrev_b32_e32 v227, 4, v227
	v_mad_u32_u24 v227, v225, s58, v227
	v_add_u32_e32 v227, v227, v226
	v_lshrrev_b32_e32 v225, 1, v224
	v_and_b32_e32 v224, 1, v224
	v_lshlrev_b32_e32 v224, 5, v224
	v_mad_u32_u24 v224, v225, s58, v224
	v_add_u32_e32 v224, v224, v226
	ds_write_b128 v227, v[80:83]
	ds_write_b128 v227, v[84:87] offset:1152
	ds_write_b128 v227, v[88:91] offset:2304
	ds_write_b128 v227, v[92:95] offset:3456
	ds_read_b128 v[80:83], v224
	ds_read_b128 v[84:87], v224 offset:16
	ds_read_b128 v[92:95], v224 offset:64
	ds_read_b128 v[88:91], v224 offset:80
	s_waitcnt lgkmcnt(0)
	v_and_b32_e32 v64, 0xffff0000, v84
	v_lshlrev_b32_e32 v65, 16, v84
	v_and_b32_e32 v60, 0xffff0000, v85
	v_lshlrev_b32_e32 v61, 16, v85
	s_add_i32 s97, s97, s55
	v_or_b32_e32 v8, s89, v185
	v_and_b32_e32 v66, 0xffff0000, v88
	v_lshlrev_b32_e32 v67, 16, v88
	v_and_b32_e32 v62, 0xffff0000, v89
	v_lshlrev_b32_e32 v63, 16, v89
	v_pk_mul_f32 v[0:1], v[64:65], v[64:65]
	v_pk_mul_f32 v[2:3], v[60:61], v[60:61]
	v_or_b32_e32 v8, s68, v8
	s_lshl_b32 s94, s97, 7
	v_and_b32_e32 v56, 0xffff0000, v86
	v_lshlrev_b32_e32 v57, 16, v86
	v_and_b32_e32 v52, 0xffff0000, v87
	v_lshlrev_b32_e32 v53, 16, v87
	v_pk_fma_f32 v[214:215], v[66:67], v[66:67], v[0:1]
	v_pk_fma_f32 v[216:217], v[62:63], v[62:63], v[2:3]
	v_or_b32_e32 v2, 32, v8
	v_and_b32_e32 v58, 0xffff0000, v90
	v_lshlrev_b32_e32 v59, 16, v90
	v_and_b32_e32 v54, 0xffff0000, v91
	v_lshlrev_b32_e32 v55, 16, v91
	v_pk_mul_f32 v[4:5], v[56:57], v[56:57]
	v_pk_mul_f32 v[6:7], v[52:53], v[52:53]
	v_pk_fma_f32 v[218:219], v[58:59], v[58:59], v[4:5]
	v_pk_fma_f32 v[220:221], v[54:55], v[54:55], v[6:7]
	v_readlane_b32 s78, v255, 6
	v_readlane_b32 s79, v255, 7
	s_or_b32 s58, s89, s68
	s_or_b32 s58, s58, s91
	v_and_b32_e32 v231, 7, v250
	v_add_u32_e32 v231, s58, v231
	v_add_u32_e32 v230, s94, v248
	v_mad_u32_u24 v230, v231, s65, v230
	s_nop 0
	global_load_dwordx4 v[0:3], v230, s[78:79]
	v_add_u32_e32 v230, 0x6000, v230
	global_load_dwordx4 v[4:7], v230, s[78:79]
	v_add_u32_e32 v230, 0x6000, v230
	global_load_dwordx4 v[8:11], v230, s[78:79]
	v_add_u32_e32 v230, 0x6000, v230
	global_load_dwordx4 v[12:15], v230, s[78:79]
	v_add_u32_e32 v230, 0x6000, v230
	global_load_dwordx4 v[100:103], v230, s[78:79]
	v_add_u32_e32 v230, 0x6000, v230
	global_load_dwordx4 v[104:107], v230, s[78:79]
	v_add_u32_e32 v230, 0x6000, v230
	global_load_dwordx4 v[108:111], v230, s[78:79]
	v_add_u32_e32 v230, 0x6000, v230
	global_load_dwordx4 v[112:115], v230, s[78:79]
	v_lshlrev_b32_e32 v239, 16, v92
	v_lshlrev_b32_e32 v238, 16, v80
	v_and_b32_e32 v245, 0xffff0000, v92
	v_and_b32_e32 v244, 0xffff0000, v80
	v_lshlrev_b32_e32 v229, 16, v93
	v_lshlrev_b32_e32 v228, 16, v81
	v_pk_mul_f32 v[240:241], v[238:239], v[238:239]
	v_pk_mul_f32 v[246:247], v[244:245], v[244:245]
	v_pk_mul_f32 v[230:231], v[228:229], v[228:229]
	v_and_b32_e32 v235, 0xffff0000, v93
	v_and_b32_e32 v234, 0xffff0000, v81
	v_lshlrev_b32_e32 v171, 16, v94
	v_lshlrev_b32_e32 v170, 16, v82
	v_pk_mul_f32 v[236:237], v[234:235], v[234:235]
	v_and_b32_e32 v173, 0xffff0000, v94
	v_and_b32_e32 v172, 0xffff0000, v82
	v_pk_mul_f32 v[178:179], v[170:171], v[170:171]
	v_lshlrev_b32_e32 v167, 16, v95
	v_lshlrev_b32_e32 v166, 16, v83
	v_pk_mul_f32 v[180:181], v[172:173], v[172:173]
	v_and_b32_e32 v169, 0xffff0000, v95
	v_and_b32_e32 v168, 0xffff0000, v83
	v_pk_mul_f32 v[174:175], v[166:167], v[166:167]
	v_pk_mul_f32 v[176:177], v[168:169], v[168:169]
	v_readlane_b32 s76, v255, 1
	s_add_i32 s33, s33, s76
	v_readlane_b32 s77, v255, 2
	s_cmpk_gt_i32 s33, 0x3ff
	s_cselect_b64 s[76:77], -1, 0
	s_waitcnt lgkmcnt(0)
	v_mov_b32_e32 v98, v26
	s_waitcnt lgkmcnt(0)
	v_mov_b32_e32 v223, v28
	v_add_f32_e32 v26, v247, v246
	v_add_f32_e32 v28, v241, v240
	v_add_f32_e32 v26, v28, v26
	v_add_f32_e32 v28, v231, v230
	v_mov_b32_e32 v222, v24
	v_add_f32_e32 v24, v237, v236
	v_add_f32_e32 v26, v28, v26
	v_add_f32_e32 v24, v24, v26
	v_add_f32_e32 v26, v179, v178
	v_add_f32_e32 v24, v26, v24
	v_add_f32_e32 v26, v181, v180
	v_add_f32_e32 v24, v26, v24
	v_add_f32_e32 v26, v175, v174
	v_add_f32_e32 v24, v26, v24
	v_add_f32_e32 v26, v177, v176
	v_add_f32_e32 v24, v26, v24
	v_add_f32_e32 v24, v215, v24
	v_add_f32_e32 v24, v214, v24
	v_add_f32_e32 v24, v217, v24
	v_add_f32_e32 v24, v216, v24
	v_add_f32_e32 v24, v219, v24
	v_add_f32_e32 v24, v218, v24
	v_add_f32_e32 v24, v221, v24
	v_add_f32_e32 v24, v220, v24
	s_waitcnt vmcnt(8)
	ds_write_b128 v227, v[116:119]
	ds_write_b128 v227, v[44:47] offset:1152
	ds_write_b128 v227, v[158:161] offset:2304
	ds_write_b128 v227, v[40:43] offset:3456
	v_and_b32_e32 v225, 63, v251
	v_lshrrev_b32_e32 v224, 1, v225
	v_and_b32_e32 v225, 1, v225
	v_lshlrev_b32_e32 v225, 6, v225
	v_mul_u32_u24_e32 v224, 0x90, v224
	v_add3_u32 v225, v224, v225, v226
	ds_read_b128 v[116:119], v225
	ds_read_b128 v[44:47], v225 offset:16
	ds_read_b128 v[158:161], v225 offset:32
	ds_read_b128 v[40:43], v225 offset:48
	ds_write_b128 v227, v[154:157]
	ds_write_b128 v227, v[68:71] offset:1152
	ds_write_b128 v227, v[162:165] offset:2304
	ds_write_b128 v227, v[48:51] offset:3456
	ds_read_b128 v[154:157], v225
	ds_read_b128 v[68:71], v225 offset:16
	ds_read_b128 v[162:165], v225 offset:32
	ds_read_b128 v[48:51], v225 offset:48
	s_waitcnt lgkmcnt(0)
	s_waitcnt lgkmcnt(0)
	v_mov_b32_e32 v176, v72
	s_waitcnt lgkmcnt(0)
	v_mov_b32_e32 v177, v76
	v_mov_b32_e32 v178, v116
	v_mov_b32_e32 v179, v154
	s_waitcnt lgkmcnt(0)
	s_nop 1
	v_add_f32_dpp v24, v24, v24 quad_perm:[1,0,3,2] row_mask:0xf bank_mask:0xf
	v_fmamk_f32 v24, v24, 0x3c800000, v189
	v_rsq_f32_e32 v24, v24
	v_mov_b32_e32 v76, v73
	v_mov_b32_e32 v232, v74
	v_mov_b32_e32 v233, v78
	v_pk_mul_f32 v[180:181], v[24:25], v[238:239] op_sel_hi:[0,1]
	v_pk_mul_f32 v[176:177], v[176:177], v[180:181]
	v_mov_b32_e32 v174, v118
	v_pk_mul_f32 v[178:179], v[178:179], v[176:177]
	v_mov_b32_e32 v175, v156
	v_sub_f32_e32 v96, v178, v179
	v_mov_b32_e32 v178, v154
	v_mov_b32_e32 v179, v116
	v_pk_mul_f32 v[176:177], v[178:179], v[176:177]
	v_mov_b32_e32 v154, v117
	v_add_f32_e32 v153, v177, v176
	v_pk_mul_f32 v[176:177], v[24:25], v[244:245] op_sel_hi:[0,1]
	v_pk_mul_f32 v[72:73], v[76:77], v[176:177]
	v_mov_b32_e32 v116, v155
	v_pk_mul_f32 v[76:77], v[154:155], v[72:73]
	v_pk_mul_f32 v[72:73], v[116:117], v[72:73]
	v_sub_f32_e32 v154, v76, v77
	v_add_f32_e32 v116, v73, v72
	v_pk_mul_f32 v[72:73], v[24:25], v[228:229] op_sel_hi:[0,1]
	v_pk_mul_f32 v[72:73], v[232:233], v[72:73]
	v_mov_b32_e32 v78, v75
	v_pk_mul_f32 v[76:77], v[174:175], v[72:73]
	v_mov_b32_e32 v226, v44
	v_sub_f32_e32 v117, v76, v77
	v_mov_b32_e32 v76, v156
	v_mov_b32_e32 v77, v118
	v_pk_mul_f32 v[72:73], v[76:77], v[72:73]
	v_mov_b32_e32 v156, v119
	v_add_f32_e32 v76, v73, v72
	v_pk_mul_f32 v[72:73], v[24:25], v[234:235] op_sel_hi:[0,1]
	v_pk_mul_f32 v[72:73], v[78:79], v[72:73]
	v_mov_b32_e32 v118, v157
	v_pk_mul_f32 v[74:75], v[156:157], v[72:73]
	v_pk_mul_f32 v[72:73], v[118:119], v[72:73]
	v_mov_b32_e32 v227, v68
	v_add_f32_e32 v78, v73, v72
	v_pk_mul_f32 v[72:73], v[24:25], v[170:171] op_sel_hi:[0,1]
	v_pk_mul_f32 v[72:73], v[72:73], v[222:223]
	v_sub_f32_e32 v77, v74, v75
	v_pk_mul_f32 v[74:75], v[72:73], v[226:227]
	v_mov_b32_e32 v28, v25
	v_sub_f32_e32 v79, v74, v75
	v_mov_b32_e32 v74, v68
	v_mov_b32_e32 v75, v44
	v_pk_mul_f32 v[72:73], v[72:73], v[74:75]
	v_mov_b32_e32 v68, v45
	v_add_f32_e32 v74, v73, v72
	v_pk_mul_f32 v[72:73], v[24:25], v[172:173] op_sel_hi:[0,1]
	v_pk_mul_f32 v[28:29], v[72:73], v[28:29]
	v_mov_b32_e32 v44, v69
	v_pk_mul_f32 v[72:73], v[28:29], v[68:69]
	v_pk_mul_f32 v[28:29], v[28:29], v[44:45]
	v_sub_f32_e32 v25, v72, v73
	v_mov_b32_e32 v99, v30
	v_add_f32_e32 v68, v29, v28
	v_pk_mul_f32 v[28:29], v[24:25], v[166:167] op_sel_hi:[0,1]
	v_mov_b32_e32 v224, v46
	v_mov_b32_e32 v225, v70
	v_pk_mul_f32 v[28:29], v[28:29], v[98:99]
	v_mov_b32_e32 v30, v27
	v_pk_mul_f32 v[44:45], v[28:29], v[224:225]
	s_and_b64 vcc, exec, s[76:77]
	v_sub_f32_e32 v69, v44, v45
	v_mov_b32_e32 v44, v70
	v_mov_b32_e32 v45, v46
	v_pk_mul_f32 v[28:29], v[28:29], v[44:45]
	v_mov_b32_e32 v70, v47
	v_add_f32_e32 v44, v29, v28
	v_pk_mul_f32 v[28:29], v[24:25], v[168:169] op_sel_hi:[0,1]
	v_pk_mul_f32 v[26:27], v[28:29], v[30:31]
	v_mov_b32_e32 v46, v71
	v_pk_mul_f32 v[28:29], v[26:27], v[70:71]
	v_pk_mul_f32 v[26:27], v[26:27], v[46:47]
	v_sub_f32_e32 v30, v28, v29
	v_add_f32_e32 v31, v27, v26
	v_mov_b32_e32 v26, v65
	v_mov_b32_e32 v27, v67
	v_pk_mul_f32 v[26:27], v[24:25], v[26:27] op_sel_hi:[0,1]
	v_mov_b32_e32 v28, v32
	v_mov_b32_e32 v29, v36
	v_pk_mul_f32 v[26:27], v[26:27], v[28:29]
	v_mov_b32_e32 v28, v158
	v_mov_b32_e32 v29, v162
	v_pk_mul_f32 v[28:29], v[26:27], v[28:29]
	v_mov_b32_e32 v65, v66
	v_sub_f32_e32 v32, v28, v29
	v_mov_b32_e32 v28, v162
	v_mov_b32_e32 v29, v158
	v_pk_mul_f32 v[26:27], v[26:27], v[28:29]
	v_mov_b32_e32 v36, v33
	v_add_f32_e32 v45, v27, v26
	v_pk_mul_f32 v[26:27], v[24:25], v[64:65] op_sel_hi:[0,1]
	v_pk_mul_f32 v[26:27], v[26:27], v[36:37]
	v_mov_b32_e32 v162, v159
	v_mov_b32_e32 v158, v163
	v_pk_mul_f32 v[28:29], v[26:27], v[162:163]
	v_pk_mul_f32 v[26:27], v[26:27], v[158:159]
	v_sub_f32_e32 v33, v28, v29
	v_add_f32_e32 v36, v27, v26
	v_mov_b32_e32 v26, v61
	v_mov_b32_e32 v27, v63
	v_pk_mul_f32 v[26:27], v[24:25], v[26:27] op_sel_hi:[0,1]
	v_mov_b32_e32 v28, v34
	v_mov_b32_e32 v29, v38
	v_pk_mul_f32 v[26:27], v[26:27], v[28:29]
	v_mov_b32_e32 v28, v160
	v_mov_b32_e32 v29, v164
	v_pk_mul_f32 v[28:29], v[26:27], v[28:29]
	v_mov_b32_e32 v61, v62
	v_sub_f32_e32 v34, v28, v29
	v_mov_b32_e32 v28, v164
	v_mov_b32_e32 v29, v160
	v_pk_mul_f32 v[26:27], v[26:27], v[28:29]
	v_mov_b32_e32 v38, v35
	v_add_f32_e32 v37, v27, v26
	v_pk_mul_f32 v[26:27], v[24:25], v[60:61] op_sel_hi:[0,1]
	v_pk_mul_f32 v[26:27], v[26:27], v[38:39]
	v_mov_b32_e32 v164, v161
	v_mov_b32_e32 v160, v165
	v_pk_mul_f32 v[28:29], v[26:27], v[164:165]
	v_pk_mul_f32 v[26:27], v[26:27], v[160:161]
	v_sub_f32_e32 v35, v28, v29
	v_add_f32_e32 v38, v27, v26
	v_mov_b32_e32 v26, v57
	v_mov_b32_e32 v27, v59
	v_pk_mul_f32 v[26:27], v[24:25], v[26:27] op_sel_hi:[0,1]
	v_mov_b32_e32 v28, v16
	v_mov_b32_e32 v29, v20
	v_pk_mul_f32 v[26:27], v[26:27], v[28:29]
	v_mov_b32_e32 v28, v40
	v_mov_b32_e32 v29, v48
	v_pk_mul_f32 v[28:29], v[26:27], v[28:29]
	v_mov_b32_e32 v57, v58
	v_sub_f32_e32 v39, v28, v29
	v_mov_b32_e32 v28, v48
	v_mov_b32_e32 v29, v40
	v_pk_mul_f32 v[26:27], v[26:27], v[28:29]
	v_mov_b32_e32 v20, v17
	v_add_f32_e32 v28, v27, v26
	v_pk_mul_f32 v[26:27], v[24:25], v[56:57] op_sel_hi:[0,1]
	v_pk_mul_f32 v[16:17], v[26:27], v[20:21]
	v_mov_b32_e32 v48, v41
	v_mov_b32_e32 v40, v49
	v_pk_mul_f32 v[20:21], v[16:17], v[48:49]
	v_pk_mul_f32 v[16:17], v[16:17], v[40:41]
	v_sub_f32_e32 v26, v20, v21
	v_add_f32_e32 v27, v17, v16
	v_mov_b32_e32 v16, v53
	v_mov_b32_e32 v17, v55
	v_pk_mul_f32 v[16:17], v[24:25], v[16:17] op_sel_hi:[0,1]
	v_mov_b32_e32 v20, v18
	v_mov_b32_e32 v21, v22
	v_pk_mul_f32 v[16:17], v[16:17], v[20:21]
	v_mov_b32_e32 v20, v42
	v_mov_b32_e32 v21, v50
	v_pk_mul_f32 v[20:21], v[16:17], v[20:21]
	v_mov_b32_e32 v53, v54
	v_sub_f32_e32 v29, v20, v21
	v_mov_b32_e32 v20, v50
	v_mov_b32_e32 v21, v42
	v_pk_mul_f32 v[16:17], v[16:17], v[20:21]
	v_mov_b32_e32 v22, v19
	v_add_f32_e32 v20, v17, v16
	v_pk_mul_f32 v[16:17], v[24:25], v[52:53] op_sel_hi:[0,1]
	v_pk_mul_f32 v[16:17], v[16:17], v[22:23]
	v_mov_b32_e32 v50, v43
	v_mov_b32_e32 v42, v51
	v_pk_mul_f32 v[18:19], v[16:17], v[50:51]
	v_pk_mul_f32 v[16:17], v[16:17], v[42:43]
	v_sub_f32_e32 v21, v18, v19
	v_add_f32_e32 v22, v17, v16
	v_cvt_pk_bf16_f32 v16, v96, v154
	v_cvt_pk_bf16_f32 v17, v117, v77
	v_cvt_pk_bf16_f32 v18, v79, v25
	v_cvt_pk_bf16_f32 v19, v69, v30
	s_barrier
	ds_write_b128 v190, v[16:19]
	v_cvt_pk_bf16_f32 v16, v32, v33
	v_cvt_pk_bf16_f32 v17, v34, v35
	v_cvt_pk_bf16_f32 v18, v39, v26
	v_cvt_pk_bf16_f32 v19, v29, v21
	ds_write_b128 v190, v[16:19] offset:16
	v_cvt_pk_bf16_f32 v16, v153, v116
	v_cvt_pk_bf16_f32 v17, v76, v78
	v_cvt_pk_bf16_f32 v18, v74, v68
	v_cvt_pk_bf16_f32 v19, v44, v31
	ds_write_b128 v190, v[16:19] offset:64
	v_cvt_pk_bf16_f32 v16, v45, v36
	v_cvt_pk_bf16_f32 v17, v37, v38
	v_cvt_pk_bf16_f32 v18, v28, v27
	v_cvt_pk_bf16_f32 v19, v20, v22
	ds_write_b128 v190, v[16:19] offset:80
	v_and_b32_e32 v20, 63, v251
	v_lshrrev_b32_e32 v21, 3, v20
	v_mul_u32_u24_e32 v21, 0x90, v21
	v_and_b32_e32 v22, 7, v20
	v_lshl_add_u32 v21, v22, 4, v21
	v_mul_u32_u24_e32 v22, 0x1200, v254
	v_add_u32_e32 v22, 0x12000, v22
	v_add_u32_e32 v21, v21, v22
	v_lshrrev_b32_e32 v23, 2, v20
	v_mul_u32_u24_e32 v23, 0x120, v23
	v_and_b32_e32 v20, 3, v20
	v_lshl_add_u32 v23, v20, 3, v23
	v_add_u32_e32 v23, v23, v22
	ds_write_b128 v21, v[122:125]
	ds_write_b128 v21, v[128:131] offset:1152
	ds_write_b128 v21, v[132:135] offset:2304
	ds_write_b128 v21, v[136:139] offset:3456
	ds_read_b64 v[122:123], v23
	ds_read_b64 v[124:125], v23 offset:32
	ds_read_b64 v[128:129], v23 offset:64
	ds_read_b64 v[130:131], v23 offset:96
	ds_read_b64 v[132:133], v23 offset:144
	ds_read_b64 v[136:137], v23 offset:176
	ds_read_b64 v[138:139], v23 offset:208
	ds_read_b64 v[140:141], v23 offset:240
	s_waitcnt lgkmcnt(0)
	v_and_b32_e32 v16, 0xffff, v122
	v_lshrrev_b32_e32 v17, 16, v122
	v_lshl_or_b32 v16, v132, 16, v16
	v_and_or_b32 v17, v132, s54, v17
	v_add_u32_e32 v18, 0x9000, v191
	ds_write2_b32 v18, v16, v17 offset1:130
	v_and_b32_e32 v16, 0xffff, v123
	v_lshrrev_b32_e32 v17, 16, v123
	v_lshl_or_b32 v16, v133, 16, v16
	v_and_or_b32 v17, v133, s54, v17
	v_add_u32_e32 v18, 0x9400, v191
	ds_write2_b32 v18, v16, v17 offset0:4 offset1:134
	v_and_b32_e32 v16, 0xffff, v124
	v_lshrrev_b32_e32 v17, 16, v124
	v_lshl_or_b32 v16, v136, 16, v16
	v_and_or_b32 v17, v136, s54, v17
	v_add_u32_e32 v18, 0xb000, v191
	ds_write2_b32 v18, v16, v17 offset0:32 offset1:162
	v_and_b32_e32 v16, 0xffff, v125
	v_lshrrev_b32_e32 v17, 16, v125
	v_lshl_or_b32 v16, v137, 16, v16
	v_and_or_b32 v17, v137, s54, v17
	v_add_u32_e32 v18, 0xb400, v191
	ds_write2_b32 v18, v16, v17 offset0:36 offset1:166
	v_and_b32_e32 v16, 0xffff, v128
	v_lshrrev_b32_e32 v17, 16, v128
	v_lshl_or_b32 v16, v138, 16, v16
	v_and_or_b32 v17, v138, s54, v17
	v_add_u32_e32 v18, 0xd000, v191
	ds_write2_b32 v18, v16, v17 offset0:64 offset1:194
	v_and_b32_e32 v16, 0xffff, v129
	v_lshrrev_b32_e32 v17, 16, v129
	v_lshl_or_b32 v16, v139, 16, v16
	v_and_or_b32 v17, v139, s54, v17
	v_add_u32_e32 v18, 0xd400, v191
	ds_write2_b32 v18, v16, v17 offset0:68 offset1:198
	v_and_b32_e32 v16, 0xffff, v130
	v_lshrrev_b32_e32 v17, 16, v130
	v_lshl_or_b32 v16, v140, 16, v16
	v_and_or_b32 v17, v140, s54, v17
	v_add_u32_e32 v18, 0xf000, v191
	ds_write2_b32 v18, v16, v17 offset0:96 offset1:226
	v_and_b32_e32 v16, 0xffff, v131
	v_lshrrev_b32_e32 v17, 16, v131
	v_lshl_or_b32 v16, v141, 16, v16
	v_and_or_b32 v17, v141, s54, v17
	v_add_u32_e32 v18, 0xf400, v191
	ds_write2_b32 v18, v16, v17 offset0:100 offset1:230
	s_waitcnt vmcnt(0)
	v_and_b32_e32 v16, 63, v251
	v_lshrrev_b32_e32 v17, 3, v16
	v_mul_u32_u24_e32 v17, 0x90, v17
	v_and_b32_e32 v18, 7, v16
	v_lshl_add_u32 v17, v18, 4, v17
	v_mul_u32_u24_e32 v18, 0x1200, v254
	v_add_u32_e32 v18, 0x12000, v18
	v_add_u32_e32 v17, v17, v18
	v_and_b32_e32 v19, 31, v16
	v_mul_u32_u24_e32 v19, 0x90, v19
	v_lshrrev_b32_e32 v16, 5, v16
	v_lshl_add_u32 v19, v16, 4, v19
	v_add_u32_e32 v19, v19, v18
	ds_write_b128 v17, v[0:3]
	ds_write_b128 v17, v[4:7] offset:1152
	ds_write_b128 v17, v[8:11] offset:2304
	ds_write_b128 v17, v[12:15] offset:3456
	ds_read_b128 v[0:3], v19
	ds_read_b128 v[8:11], v19 offset:32
	ds_read_b128 v[4:7], v19 offset:64
	ds_read_b128 v[12:15], v19 offset:96
	ds_write_b128 v17, v[100:103]
	ds_write_b128 v17, v[104:107] offset:1152
	ds_write_b128 v17, v[108:111] offset:2304
	ds_write_b128 v17, v[112:115] offset:3456
	ds_read_b128 v[100:103], v19
	ds_read_b128 v[108:111], v19 offset:32
	ds_read_b128 v[104:107], v19 offset:64
	ds_read_b128 v[112:115], v19 offset:96
	s_waitcnt lgkmcnt(0)
	s_cbranch_vccnz .LBB0_354
	s_add_i32 s64, s1, s96
	s_and_b32 s64, s64, 0x780
	s_addk_i32 s64, 0xff80
	v_mov_b32_e32 v96, v97
	v_add_u32_e32 v16, s64, v182
	v_mov_b32_e32 v98, v97
	v_mov_b32_e32 v99, v97
	v_mov_b64_e32 v[80:81], v[96:97]
	v_mov_b64_e32 v[84:85], v[96:97]
	v_mov_b64_e32 v[92:93], v[96:97]
	v_mov_b64_e32 v[88:89], v[96:97]
	s_ashr_i32 s55, s33, 6
	s_and_b32 s69, s33, 3
	v_cmp_lt_i32_e32 vcc, -1, v16
	v_mov_b64_e32 v[82:83], v[98:99]
	v_mov_b64_e32 v[86:87], v[98:99]
	v_mov_b64_e32 v[94:95], v[98:99]
	v_mov_b64_e32 v[90:91], v[98:99]
	s_and_saveexec_b64 s[78:79], vcc
	s_cbranch_execz .LBB0_351
	v_readlane_b32 vcc_lo, v255, 6
	v_readlane_b32 vcc_hi, v255, 7
	v_add_u32_e32 v18, s64, v250
	v_lshl_add_u32 v18, s55, 11, v18
	s_lshl_b32 s94, s69, 7
	v_mov_b64_e32 v[16:17], vcc
	v_mad_i64_i32 v[16:17], vcc, v18, s65, v[16:17]
	v_lshl_add_u64 v[16:17], v[16:17], 0, s[94:95]
	v_mov_b32_e32 v153, v97
	v_lshl_add_u64 v[16:17], v[16:17], 0, v[248:249]
	s_movk_i32 s94, 0x6000
	global_load_dwordx4 v[80:83], v[16:17], off offset:2048
	v_lshl_add_u64 v[16:17], v[16:17], 0, s[94:95]
	global_load_dwordx4 v[84:87], v[16:17], off offset:2048
	v_lshl_add_u64 v[16:17], v[16:17], 0, s[94:95]
	global_load_dwordx4 v[88:91], v[16:17], off offset:2048
	v_lshl_add_u64 v[16:17], v[16:17], 0, s[94:95]
	global_load_dwordx4 v[92:95], v[16:17], off offset:2048
